# seventh XCC-local barrier instance: invalidate before the arrival atomic; stacked
# speedup vs baseline: 1.0113x; 1.0016x over previous
; __device__ __forceinline__ unsigned xb_ld(unsigned* p)              { return __hip_atomic_load(p, __ATOMIC_RELAXED, __HIP_MEMORY_SCOPE_AGENT); }
; __device__ __forceinline__ unsigned xb_add(unsigned* p, unsigned v) { return __hip_atomic_fetch_add(p, v, __ATOMIC_RELAXED, __HIP_MEMORY_SCOPE_AGENT); }
; #define XB_SPIN(cond, bar) do { unsigned _sp = 0; while (cond) { __builtin_amdgcn_s_sleep(1); \
;     if ((++_sp & 255u) == 0u) { if (xb_ld(&(bar)[XB_TMO])) break; if (_sp > XB_SPIN_CAP) { atomicAdd(&(bar)[XB_TMO], 1u); break; } } } } while (0)
; #define x (arg_in(0))
; __device__ __forceinline__ void xcd_local_barrier(const XcdBarrier& b) {
;     ...
;         if (old + 1u == (gen + 1u) * nloc) xb_add(&bar[XB_XGEN2(b.x)], 1u);
;         else XB_SPIN(xb_ld(&bar[XB_XGEN2(b.x)]) == gen, bar);
;         __builtin_amdgcn_fence(__ATOMIC_ACQUIRE, "agent");
;         asm volatile("s_waitcnt vmcnt(0)" ::: "memory");
.LBB0_53:
	s_or_b64 exec, exec, s[40:41]
	s_waitcnt vmcnt(0)
	s_waitcnt vmcnt(0)

; __device__ __forceinline__ unsigned xb_add(unsigned* p, unsigned v) { return __hip_atomic_fetch_add(p, v, __ATOMIC_RELAXED, __HIP_MEMORY_SCOPE_AGENT); }
; #define x (arg_in(0))
; __device__ __forceinline__ void xcd_local_barrier(const XcdBarrier& b) {
;     ...
;     __syncthreads();
;     if (threadIdx.x == 0) {
;         unsigned* bar = b.bar;
;         __builtin_amdgcn_s_waitcnt(0);
;         unsigned nloc = b.st[0], nx = b.st[1];
;         if (nloc == 0u) { xcd_barrier_complete(bar, b.x, nloc, nx); b.st[0] = nloc; b.st[1] = nx; }
;         const unsigned old = xb_add(&bar[XB_XSUB2(b.x)], 1u);
;         const unsigned gen = old / nloc;
;         if (old + 1u == (gen + 1u) * nloc) xb_add(&bar[XB_XGEN2(b.x)], 1u);
.LBB0_1087:
	s_mov_b64 s[40:41], exec
	s_waitcnt lgkmcnt(0)
	v_mbcnt_lo_u32_b32 v1, s40, 0
	v_mbcnt_hi_u32_b32 v1, s41, v1
	v_cmp_eq_u32_e32 vcc, 0, v1
	s_and_saveexec_b64 s[36:37], vcc
	s_cbranch_execz .LBB0_1089
	s_bcnt1_i32_b64 s2, s[40:41]
	v_readlane_b32 s12, v253, 50
	v_mov_b32_e32 v2, s2
	v_readlane_b32 s13, v253, 51
	s_nop 4
	buffer_inv sc1
	global_atomic_add v2, v129, v2, s[12:13] sc0
